# MLA loop: two of the tile's four LDS-DMA pieces issued in the shadow of the first K fragment reads, the other two later in QK
# baseline (speedup 1.0000x reference)
; #define LAS __attribute__((address_space(3)))
; #define MFMA32(a, b, c) __builtin_amdgcn_mfma_f32_32x32x16_bf16((a), (b), (c), 0, 0, 0)
; DI int crow(int r, int hi) { return (r & 3) + 8 * (r >> 2) + 4 * hi; }
; #define MLA_DMA(t, slot) do { _Pragma("unroll") for (int i_ = 0; i_ < 4; ++i_) { const bf16_t* src_ = (pisk[i_] ? kbase : vbase) + poff[i_] + (size_t)(t) * pstep[i_]; \
;         __builtin_amdgcn_global_load_lds((const unsigned*)src_, (LAS unsigned*)(lds + (slot) * SLOT + (w + 8 * i_) * 1024), 16, 0, 0); } } while (0)
; DI void mla_attn_phase(LAS unsigned char* lds, const bf16_t* Qg, const bf16_t* Kg, const bf16_t* Vtg, bf16_t* MIX) {
;     ...
;                 const int sl2 = sl == 0 ? 2 : sl - 1;
;                 if (kt + 2 < NT) MLA_DMA(kt + 2, sl2);
;                 if (64 * kt <= q0 + 31) {
;                     const LAS bf16_t* kb = (const LAS bf16_t*)(lds + sl * SLOT); const LAS bf16_t* vb = (const LAS bf16_t*)(lds + sl * SLOT + VOFF);
;     ...
;                     bf16x8 ka0, kc0_, ka1, kc1_;
;                     KFRAG(ka0, kc0_, 0); KFRAG(ka1, kc1_, 1);
;                     __builtin_amdgcn_sched_barrier(0);
;                     f32x16 s0, s1;
; #pragma unroll
;                     for (int i = 0; i < 16; ++i) { s0[i] = 0.f; s1[i] = 0.f; }
;                     s0 = MFMA32(ka0, qf[0], s0); s1 = MFMA32(kc0_, qf[0], s1); KFRAG(ka0, kc0_, 2); __builtin_amdgcn_sched_barrier(0);
;                     s0 = MFMA32(ka1, qf[1], s0); s1 = MFMA32(kc1_, qf[1], s1); KFRAG(ka1, kc1_, 3); __builtin_amdgcn_sched_barrier(0);
;                     s0 = MFMA32(ka0, qf[2], s0); s1 = MFMA32(kc0_, qf[2], s1); KFRAG(ka0, kc0_, 4); __builtin_amdgcn_sched_barrier(0);
;                     s0 = MFMA32(ka1, qf[3], s0); s1 = MFMA32(kc1_, qf[3], s1); KFRAG(ka1, kc1_, 5); __builtin_amdgcn_sched_barrier(0);
;                     s0 = MFMA32(ka0, qf[4], s0); s1 = MFMA32(kc0_, qf[4], s1); s0 = MFMA32(ka1, qf[5], s0); s1 = MFMA32(kc1_, qf[5], s1);
;     ...
;                     bf16x8 vfa[4], vfb[4];
;                     VFRAG(vfa, 0); VFRAG(vfb, 1);
;                     __builtin_amdgcn_sched_barrier(0);
;                     if (kt >= 4 * qb) { const int qpos = q0 + r32;
; #pragma unroll
;                         for (int i = 0; i < 16; ++i) { const int key0 = 64 * kt + crow(i, hf); if (key0 > qpos) s0[i] = -INFINITY; if (key0 + 32 > qpos) s1[i] = -INFINITY; } }
.LBB0_359:
	s_add_i32 s28, s42, 2
	s_cmp_ge_i32 s28, s38
	s_cselect_b64 s[28:29], -1, 0
	s_add_i32 s31, s41, 2
	s_and_b32 s31, s31, 3
	s_lshl_b32 s31, s31, 15
	s_add_i32 s31, s35, s31
.LBB0_361:
	s_cmp_gt_i32 s40, s39
	s_cbranch_scc1 .Lmla_skip1
	s_lshl_b32 s30, s41, 15
	s_add_i32 s30, s30, 0
	v_lshlrev_b32_e32 v0, 1, v166
	v_add_u32_e32 v1, s30, v0
	v_add_u32_e32 v3, v1, v230
	s_mov_b32 m0, s31
	ds_read_b128 v[4:7], v3
	ds_read_b128 v[8:11], v3 offset:32
	ds_read_b128 v[12:15], v3 offset:6656
	ds_read_b128 v[136:139], v3 offset:6688
	global_load_lds_dwordx4 v[210:211], off
	s_add_i32 m0, s31, 0x2000
	s_nop 0
	global_load_lds_dwordx4 v[212:213], off
	s_add_i32 m0, s31, 0x4000
	s_waitcnt lgkmcnt(0)
	v_mfma_f32_32x32x16_bf16 v[80:95], v[4:7], v[112:115], 0
	ds_read_b128 v[4:7], v3 offset:64
	ds_read_b128 v[140:143], v3 offset:6720
	v_mfma_f32_32x32x16_bf16 v[80:95], v[8:11], v[116:119], v[80:95]
	ds_read_b128 v[8:11], v3 offset:96
	ds_read_b128 v[144:147], v3 offset:6752
	global_load_lds_dwordx4 v[214:215], off
	s_add_i32 m0, s31, 0x6000
	s_waitcnt lgkmcnt(0)
	v_mfma_f32_32x32x16_bf16 v[80:95], v[4:7], v[120:123], v[80:95]
	ds_read_b128 v[4:7], v3 offset:128
	ds_read_b128 v[148:151], v3 offset:6784
	v_mfma_f32_32x32x16_bf16 v[80:95], v[8:11], v[124:127], v[80:95]
	ds_read_b128 v[8:11], v3 offset:160
	ds_read_b128 v[236:239], v3 offset:6816
	global_load_lds_dwordx4 v[216:217], off
	v_mfma_f32_32x32x16_bf16 v[96:111], v[12:15], v[112:115], 0
	v_add_u32_e32 v1, v1, v232
	v_mfma_f32_32x32x16_bf16 v[96:111], v[136:139], v[116:119], v[96:111]
	v_mfma_f32_32x32x16_bf16 v[96:111], v[140:143], v[120:123], v[96:111]
	v_mfma_f32_32x32x16_bf16 v[96:111], v[144:147], v[124:127], v[96:111]
	ds_read_b128 v[144:147], v1 offset:13312
	ds_read_b128 v[140:143], v1 offset:17920
	s_waitcnt lgkmcnt(2)
	v_mfma_f32_32x32x16_bf16 v[80:95], v[4:7], v[128:131], v[80:95]
	v_mfma_f32_32x32x16_bf16 v[96:111], v[148:151], v[128:131], v[96:111]
	ds_read_b128 v[148:151], v1 offset:22528
	ds_read_b128 v[152:155], v1 offset:27136
	v_add3_u32 v1, s30, v232, v0
	v_mfma_f32_32x32x16_bf16 v[80:95], v[8:11], v[132:135], v[80:95]
	ds_read_b128 v[136:139], v1 offset:13344
	ds_read_b128 v[12:15], v1 offset:17952
	ds_read_b128 v[4:7], v1 offset:22560
	ds_read_b128 v[8:11], v1 offset:27168
	v_mfma_f32_32x32x16_bf16 v[96:111], v[236:239], v[132:135], v[96:111]
	s_cmp_lt_i32 s42, s8
	s_cbranch_scc1 .LBB0_364
	v_add_u32_e32 v0, s40, v231
	v_add_u32_e32 v3, 32, v0
	v_cmp_le_i32_e32 vcc, v3, v167
	v_add_u32_e32 v3, 33, v0
	s_nop 5
	v_cndmask_b32_e32 v96, v229, v96, vcc
	v_cmp_lt_i32_e32 vcc, v0, v167
	s_nop 1
	v_cndmask_b32_e32 v81, v229, v81, vcc
	v_cmp_le_i32_e32 vcc, v0, v167
	s_nop 1
	v_cndmask_b32_e32 v80, v229, v80, vcc
	v_cmp_le_i32_e32 vcc, v3, v167
	v_add_u32_e32 v3, 2, v0
	s_nop 0
	v_cndmask_b32_e32 v97, v229, v97, vcc
	v_cmp_le_i32_e32 vcc, v3, v167
	v_add_u32_e32 v3, 34, v0
	s_nop 0
	v_cndmask_b32_e32 v82, v229, v82, vcc
	v_cmp_le_i32_e32 vcc, v3, v167
	v_add_u32_e32 v3, 3, v0
	s_nop 0
	v_cndmask_b32_e32 v98, v229, v98, vcc
	v_cmp_le_i32_e32 vcc, v3, v167
	v_add_u32_e32 v3, 35, v0
	s_nop 0
	v_cndmask_b32_e32 v83, v229, v83, vcc
	v_cmp_le_i32_e32 vcc, v3, v167
	v_add_u32_e32 v3, 8, v0
	s_nop 0
	v_cndmask_b32_e32 v99, v229, v99, vcc
	v_cmp_le_i32_e32 vcc, v3, v167
	v_add_u32_e32 v3, 40, v0
	s_nop 0
	v_cndmask_b32_e32 v84, v229, v84, vcc
	v_cmp_le_i32_e32 vcc, v3, v167
	v_add_u32_e32 v3, 9, v0
	s_nop 0
	v_cndmask_b32_e32 v100, v229, v100, vcc
	v_cmp_le_i32_e32 vcc, v3, v167
	v_add_u32_e32 v3, 41, v0
	s_nop 0
	v_cndmask_b32_e32 v85, v229, v85, vcc
	v_cmp_le_i32_e32 vcc, v3, v167
	v_add_u32_e32 v3, 10, v0
	s_nop 0
	v_cndmask_b32_e32 v101, v229, v101, vcc
	v_cmp_le_i32_e32 vcc, v3, v167
	v_add_u32_e32 v3, 42, v0
	s_nop 0
	v_cndmask_b32_e32 v86, v229, v86, vcc
	v_cmp_le_i32_e32 vcc, v3, v167
	v_add_u32_e32 v3, 11, v0
	s_nop 0
	v_cndmask_b32_e32 v102, v229, v102, vcc
	v_cmp_le_i32_e32 vcc, v3, v167
	v_add_u32_e32 v3, 43, v0
	s_nop 0
	v_cndmask_b32_e32 v87, v229, v87, vcc
	v_cmp_le_i32_e32 vcc, v3, v167
	v_add_u32_e32 v3, 16, v0
	s_nop 0
	v_cndmask_b32_e32 v103, v229, v103, vcc
	v_cmp_le_i32_e32 vcc, v3, v167
	v_add_u32_e32 v3, 48, v0
	s_nop 0
	v_cndmask_b32_e32 v88, v229, v88, vcc
	v_cmp_le_i32_e32 vcc, v3, v167
	v_add_u32_e32 v3, 17, v0
	s_nop 0
	v_cndmask_b32_e32 v104, v229, v104, vcc
	v_cmp_le_i32_e32 vcc, v3, v167
	v_add_u32_e32 v3, 49, v0
	s_nop 0
	v_cndmask_b32_e32 v89, v229, v89, vcc
	v_cmp_le_i32_e32 vcc, v3, v167
	v_add_u32_e32 v3, 18, v0
	s_nop 0
	v_cndmask_b32_e32 v105, v229, v105, vcc
	v_cmp_le_i32_e32 vcc, v3, v167
	v_add_u32_e32 v3, 50, v0
	s_nop 0
	v_cndmask_b32_e32 v90, v229, v90, vcc
	v_cmp_le_i32_e32 vcc, v3, v167
	v_add_u32_e32 v3, 19, v0
	s_nop 0
	v_cndmask_b32_e32 v106, v229, v106, vcc
	v_cmp_le_i32_e32 vcc, v3, v167
	v_add_u32_e32 v3, 51, v0
	s_nop 0
	v_cndmask_b32_e32 v91, v229, v91, vcc
	v_cmp_le_i32_e32 vcc, v3, v167
	v_add_u32_e32 v3, 24, v0
	s_nop 0
	v_cndmask_b32_e32 v107, v229, v107, vcc
	v_cmp_le_i32_e32 vcc, v3, v167
	v_add_u32_e32 v3, 56, v0
	s_nop 0
	v_cndmask_b32_e32 v92, v229, v92, vcc
	v_cmp_le_i32_e32 vcc, v3, v167
	v_add_u32_e32 v3, 25, v0
	s_nop 0
	v_cndmask_b32_e32 v108, v229, v108, vcc
	v_cmp_le_i32_e32 vcc, v3, v167
	v_add_u32_e32 v3, 57, v0
	s_nop 0
	v_cndmask_b32_e32 v93, v229, v93, vcc
	v_cmp_le_i32_e32 vcc, v3, v167
	v_add_u32_e32 v3, 26, v0
	s_nop 0
	v_cndmask_b32_e32 v109, v229, v109, vcc
	v_cmp_le_i32_e32 vcc, v3, v167
	v_add_u32_e32 v3, 58, v0
	s_nop 0
	v_cndmask_b32_e32 v94, v229, v94, vcc
	v_cmp_le_i32_e32 vcc, v3, v167
	v_add_u32_e32 v3, 27, v0
	v_add_u32_e32 v0, 59, v0
	v_cndmask_b32_e32 v110, v229, v110, vcc
	v_cmp_le_i32_e32 vcc, v3, v167
	s_nop 1
	v_cndmask_b32_e32 v95, v229, v95, vcc
	v_cmp_le_i32_e32 vcc, v0, v167
	s_nop 1
	v_cndmask_b32_e32 v111, v229, v111, vcc

; #define MLA_DMA(t, slot) do { _Pragma("unroll") for (int i_ = 0; i_ < 4; ++i_) { const bf16_t* src_ = (pisk[i_] ? kbase : vbase) + poff[i_] + (size_t)(t) * pstep[i_]; \
;         __builtin_amdgcn_global_load_lds((const unsigned*)src_, (LAS unsigned*)(lds + (slot) * SLOT + (w + 8 * i_) * 1024), 16, 0, 0); } } while (0)
; DI void mla_attn_phase(LAS unsigned char* lds, const bf16_t* Qg, const bf16_t* Kg, const bf16_t* Vtg, bf16_t* MIX) {
;     ...
;                 if (kt + 2 < NT) MLA_DMA(kt + 2, sl2);
.Lmla_skip1:
	s_mov_b32 m0, s31
	s_nop 0
	global_load_lds_dwordx4 v[210:211], off
	s_add_i32 m0, s31, 0x2000
	s_nop 0
	global_load_lds_dwordx4 v[212:213], off
	s_add_i32 m0, s31, 0x4000
	s_nop 0
	global_load_lds_dwordx4 v[214:215], off
	s_add_i32 m0, s31, 0x6000
	s_nop 0
	global_load_lds_dwordx4 v[216:217], off
	s_branch .Lmla_mid
